# P4 unit order: the 32 context units go two each to the 16 workgroups with the short neighbourhood units (grid-row block 0/31) instead of one each on top of a full load; second NA unit reuses the first
# speedup vs baseline: 1.0077x; 1.0016x over previous
;     ...
;     for (int i = F.tid; i < 1024; i += NWAVES * 64) {
;         gl[i] = gw_[i];
; #pragma unroll
;         for (int cnd = 0; cnd < 3; ++cnd) {
;             float sh, sc;
;             if (from_partials) { sh = ada_b[layer * 6144 + offsh + i]; sc = ada_b[layer * 6144 + offsc + i];
;                 float ph[ADA_KS], pc[ADA_KS];
; #pragma unroll
;                 for (int ks = 0; ks < ADA_KS; ++ks) { const float* p = modp + ((size_t)(ks * 2 + layer) * 3 + cnd) * 6144; ph[ks] = p[offsh + i]; pc[ks] = p[offsc + i]; }
; #pragma unroll
;                 for (int ks = 0; ks < ADA_KS; ++ks) { sh += ph[ks]; sc += pc[ks]; } }
;             else { sh = mod[(layer * 3 + cnd) * 6144 + offsh + i]; sc = mod[(layer * 3 + cnd) * 6144 + offsc + i]; }
;             scl[cnd * 1024 + i] = 1.f + sc; shl[cnd * 1024 + i] = sh;
;         }
;     }
.LBB0_153:
	v_lshlrev_b32_e32 v220, 2, v2
	v_lshlrev_b32_e32 v221, 2, v3
	global_load_dword v236, v220, s[4:5]
	global_load_dword v237, v221, s[4:5]
	v_add_u32_e32 v222, s12, v220
	v_add_u32_e32 v223, s12, v221
	global_load_dword v228, v222, s[8:9] offset:-4096
	global_load_dword v229, v223, s[8:9] offset:-4096
	global_load_dword v230, v222, s[8:9]
	global_load_dword v231, v223, s[8:9]
	v_add_u32_e32 v222, s13, v220
	v_add_u32_e32 v223, s13, v221
	global_load_dword v232, v222, s[8:9] offset:-4096
	global_load_dword v233, v223, s[8:9] offset:-4096
	global_load_dword v234, v222, s[8:9]
	global_load_dword v235, v223, s[8:9]
	v_add_u32_e32 v222, s14, v220
	v_add_u32_e32 v223, s14, v221
	global_load_dword v238, v222, s[8:9] offset:-4096
	global_load_dword v239, v223, s[8:9] offset:-4096
	global_load_dword v240, v222, s[8:9]
	global_load_dword v241, v223, s[8:9]
	v_add_u32_e32 v7, -2, v7
	v_add_u32_e32 v224, 0x400, v2
	v_add_u32_e32 v225, 0x400, v3
	v_lshl_add_u32 v226, v224, 2, 0
	v_lshl_add_u32 v227, v225, 2, 0
	v_cmp_eq_u32_e32 vcc, 0, v7
	s_or_b64 s[10:11], vcc, s[10:11]
	s_waitcnt vmcnt(0)
	ds_write2st64_b32 v8, v236, v237 offset1:8
	v_add_f32_e32 v230, 1.0, v230
	v_add_f32_e32 v231, 1.0, v231
	ds_write2st64_b32 v8, v230, v231 offset0:16 offset1:24
	ds_write2st64_b32 v8, v228, v229 offset0:64 offset1:72
	v_add_f32_e32 v234, 1.0, v234
	v_add_f32_e32 v235, 1.0, v235
	ds_write_b32 v226, v234 offset:4096
	ds_write_b32 v227, v235 offset:4096
	ds_write_b32 v226, v232 offset:16384
	ds_write_b32 v227, v233 offset:16384
	v_add_f32_e32 v240, 1.0, v240
	v_add_f32_e32 v241, 1.0, v241
	ds_write_b32 v220, v240 offset:12288
	ds_write_b32 v221, v241 offset:12288
	ds_write_b32 v220, v238 offset:24576
	ds_write_b32 v221, v239 offset:24576
	v_add_u32_e32 v8, 0x1000, v8
	v_mov_b32_e32 v2, v224
	v_mov_b32_e32 v3, v225
	s_andn2_b64 exec, exec, s[10:11]
	s_cbranch_execnz .LBB0_153
	s_nop 0
	s_nop 0
	s_nop 0
	s_nop 0
	s_nop 0
	s_or_b64 exec, exec, s[10:11]
	v_cmp_ne_u32_e32 vcc, v0, v6
	v_lshl_add_u32 v2, v6, 9, v170
	s_orn2_b64 s[8:9], vcc, exec

;     ...
;     for (int i = F.tid; i < 1024; i += NWAVES * 64) {
;         gl[i] = gw_[i];
; #pragma unroll
;         for (int cnd = 0; cnd < 3; ++cnd) {
;             float sh, sc;
;             if (from_partials) { sh = ada_b[layer * 6144 + offsh + i]; sc = ada_b[layer * 6144 + offsc + i];
;                 float ph[ADA_KS], pc[ADA_KS];
; #pragma unroll
;                 for (int ks = 0; ks < ADA_KS; ++ks) { const float* p = modp + ((size_t)(ks * 2 + layer) * 3 + cnd) * 6144; ph[ks] = p[offsh + i]; pc[ks] = p[offsc + i]; }
; #pragma unroll
;                 for (int ks = 0; ks < ADA_KS; ++ks) { sh += ph[ks]; sc += pc[ks]; } }
;             else { sh = mod[(layer * 3 + cnd) * 6144 + offsh + i]; sc = mod[(layer * 3 + cnd) * 6144 + offsc + i]; }
;             scl[cnd * 1024 + i] = 1.f + sc; shl[cnd * 1024 + i] = sh;
;         }
;     }
.LBB0_187:
	v_lshlrev_b32_e32 v220, 2, v2
	v_lshlrev_b32_e32 v221, 2, v3
	global_load_dword v236, v220, s[0:1]
	global_load_dword v237, v221, s[0:1]
	v_add_u32_e32 v222, s14, v220
	v_add_u32_e32 v223, s14, v221
	global_load_dword v228, v222, s[10:11] offset:-4096
	global_load_dword v229, v223, s[10:11] offset:-4096
	global_load_dword v230, v222, s[10:11]
	global_load_dword v231, v223, s[10:11]
	v_add_u32_e32 v222, s15, v220
	v_add_u32_e32 v223, s15, v221
	global_load_dword v232, v222, s[10:11] offset:-4096
	global_load_dword v233, v223, s[10:11] offset:-4096
	global_load_dword v234, v222, s[10:11]
	global_load_dword v235, v223, s[10:11]
	v_add_u32_e32 v222, s16, v220
	v_add_u32_e32 v223, s16, v221
	global_load_dword v238, v222, s[10:11] offset:-4096
	global_load_dword v239, v223, s[10:11] offset:-4096
	global_load_dword v240, v222, s[10:11]
	global_load_dword v241, v223, s[10:11]
	v_add_u32_e32 v5, -2, v5
	v_add_u32_e32 v224, 0x400, v2
	v_add_u32_e32 v225, 0x400, v3
	v_lshl_add_u32 v226, v224, 2, 0
	v_lshl_add_u32 v227, v225, 2, 0
	v_cmp_eq_u32_e32 vcc, 0, v5
	s_or_b64 s[12:13], vcc, s[12:13]
	s_waitcnt vmcnt(0)
	ds_write2st64_b32 v6, v236, v237 offset1:8
	v_add_f32_e32 v230, 1.0, v230
	v_add_f32_e32 v231, 1.0, v231
	ds_write2st64_b32 v6, v230, v231 offset0:16 offset1:24
	ds_write2st64_b32 v6, v228, v229 offset0:64 offset1:72
	v_add_f32_e32 v234, 1.0, v234
	v_add_f32_e32 v235, 1.0, v235
	ds_write_b32 v226, v234 offset:4096
	ds_write_b32 v227, v235 offset:4096
	ds_write_b32 v226, v232 offset:16384
	ds_write_b32 v227, v233 offset:16384
	v_add_f32_e32 v240, 1.0, v240
	v_add_f32_e32 v241, 1.0, v241
	ds_write_b32 v220, v240 offset:12288
	ds_write_b32 v221, v241 offset:12288
	ds_write_b32 v220, v238 offset:24576
	ds_write_b32 v221, v239 offset:24576
	v_add_u32_e32 v6, 0x1000, v6
	v_mov_b32_e32 v2, v224
	v_mov_b32_e32 v3, v225
	s_andn2_b64 exec, exec, s[12:13]
	s_cbranch_execnz .LBB0_187
	s_nop 0
	s_nop 0
	s_nop 0
	s_or_b64 exec, exec, s[12:13]
	v_cmp_ne_u32_e32 vcc, v0, v4
	v_lshl_add_u32 v2, v4, 9, v170
	s_orn2_b64 s[10:11], vcc, exec

; __device__ __forceinline__ void attn0_phase(Frame& F) {
;     ...
;     for (int ui = F.vcu; ui < 1056; ui += F.G) {
;         if (ui < 512) {
;             const int b = ui >> 8, h = (ui >> 5) & 7, R4 = ui & 31;
.LBB0_210:
	s_nop 0
	s_cmpk_ge_i32 s62, 0x400
	s_cbranch_scc1 .Lp4_ctx
	s_addk_i32 s62, 0x100
	s_cmpk_lt_i32 s62, 0x400
	s_cbranch_scc1 .Lp4_set
	s_and_b32 s0, s62, 31
	s_cmp_eq_u32 s0, 0
	s_cselect_b32 s1, 0, -1
	s_cmp_eq_u32 s0, 31
	s_cselect_b32 s1, 1, s1
	s_cmp_lt_i32 s1, 0
	s_cbranch_scc1 .LBB0_466
	s_sub_i32 s0, s62, 0x400
	s_lshr_b32 s0, s0, 5
	s_lshl_b32 s0, s0, 1
	s_add_i32 s0, s0, s1
	s_lshl_b32 s0, s0, 1
	s_add_i32 s62, s0, 0x400
	s_branch .Lp4_set
.Lp4_ctx:
	s_bitcmp1_b32 s62, 0
	s_cbranch_scc1 .LBB0_466
	s_add_i32 s62, s62, 1
.Lp4_set:
	s_lshl_b32 s96, s62, 4
	s_add_i32 s96, s96, 0xffffc000
	s_lshl_b32 s6, s62, 5
	s_add_i32 s6, s6, 0xffffc000
	s_add_i32 s8, s62, 0xfffffe00
	s_mov_b32 s9, s62

;   __device__ __forceinline__ void init() { krlo = clampi(4 * R4 - 4, 0, 120); const int krhi = clampi(4 * R4 - 1, 0, 120) + 7; nloc = krhi - krlo + 1; }
; #define ARG(k) (ldarg<k>())
; __device__ __forceinline__ void attn0_phase(Frame& F) {
;     ...
;         if (ui < 512) {
;             const int b = ui >> 8, h = (ui >> 5) & 7, R4 = ui & 31;
;             const float* rpb = ARG(17) + h * 465;
;             if (fast) {
;                 float* rl = (float*)(shm + attf::LDS_RPB);
;                 for (int i = F.tid; i < 465; i += NWAVES * 64) rl[i] = rpb[i] * att::LOG2E;
;                 __syncthreads();
;                 attf::FNa fu; fu.init((const attf::bf16*)QKV, (attf::bf16*)O, rl, b, h, R4, K6E);
;                 attf::fast_unit<8, attf::FNa, true>(fu, shm, F.tid);
.LBB0_300:
	s_andn2_b64 vcc, exec, s[0:1]
	s_cbranch_vccnz .LBB0_210
	s_and_b32 s47, s9, 31
	s_lshl_b32 s18, s47, 2
	s_bfe_u32 s19, s62, 0x30005
	s_max_u32 s63, s18, 4
	s_mul_i32 s22, s19, 0x744
	s_ashr_i32 s21, s62, 8
	s_and_b32 s20, s62, 31
	v_readlane_b32 s0, v243, 27
	s_load_dwordx2 s[2:3], s[82:83], 0x88
	s_waitcnt lgkmcnt(0)
	s_add_u32 s12, s2, s22
	v_readlane_b32 s1, v243, 28
	s_mul_i32 s46, s63, 0x7c
	s_addc_u32 s13, s3, 0
	s_andn2_b64 vcc, exec, s[0:1]
	s_mulk_i32 s47, 0x1f0
	s_cbranch_vccnz .LBB0_340
	s_mov_b64 s[0:1], exec
	s_cmpk_lt_u32 s62, 0x100
	s_cbranch_scc0 .LBB0_312
	v_readlane_b32 s4, v243, 31
	v_readlane_b32 s5, v243, 32
	s_and_b64 s[4:5], s[0:1], s[4:5]
	s_mov_b64 exec, s[4:5]
	s_cbranch_execz .LBB0_312
	s_mov_b64 s[14:15], -1
	v_mov_b32_e32 v2, v170
	v_mov_b32_e32 v0, v148
	s_mov_b64 s[10:11], exec
	v_readlane_b32 s4, v243, 45
	v_readlane_b32 s5, v243, 46
	s_and_b64 s[4:5], s[10:11], s[4:5]
	s_mov_b64 exec, s[4:5]
	s_cbranch_execz .LBB0_309
	s_mov_b64 s[14:15], 0
	v_mov_b32_e32 v0, v146
	v_mov_b32_e32 v4, v149
	v_mov_b64_e32 v[2:3], v[170:171]
